# t8 + norm row loops software-pipelined: next row's x loads prefetched into spare VGPRs at the top of each row body
# baseline (speedup 1.0000x reference)
.LBB0_459:
	s_mul_i32 s48, s8, 0xd800
	s_lshl_b64 s[4:5], s[48:49], 2
	v_readlane_b32 s6, v252, 51
	s_add_u32 s6, s6, s4
	v_readlane_b32 s4, v252, 52
	s_addc_u32 s7, s4, s5
	v_writelane_b32 v254, s6, 19
	s_mov_b32 s4, s8
	s_mul_i32 s48, s8, 0x1800
	v_writelane_b32 v254, s7, 20
	v_readlane_b32 s8, v252, 35
	v_writelane_b32 v254, s4, 21
	v_readlane_b32 s18, v252, 45
	v_readlane_b32 s19, v252, 46
	v_readlane_b32 s22, v252, 49
	v_readlane_b32 s23, v252, 50
	v_writelane_b32 v254, s5, 22
	s_lshl_b64 s[4:5], s[48:49], 2
	s_mov_b64 s[18:19], s[22:23]
	s_add_u32 s4, s18, s4
	s_addc_u32 s5, s19, s5
	v_writelane_b32 v254, s4, 23
	v_readlane_b32 s9, v252, 36
	v_readlane_b32 s10, v252, 37
	v_writelane_b32 v254, s5, 24
	v_readlane_b32 s4, v252, 12
	v_readlane_b32 s5, v252, 16
	s_lshl_b32 s4, s4, 3
	s_add_i32 s4, s4, s5
	s_cmpk_gt_i32 s4, 0x27ff
	v_readlane_b32 s11, v252, 38
	v_readlane_b32 s12, v252, 39
	v_readlane_b32 s13, v252, 40
	v_readlane_b32 s14, v252, 41
	v_readlane_b32 s15, v252, 42
	v_readlane_b32 s16, v252, 43
	v_readlane_b32 s17, v252, 44
	v_readlane_b32 s20, v252, 47
	v_readlane_b32 s21, v252, 48
	v_mbcnt_lo_u32_b32 v34, -1, 0
	v_mbcnt_hi_u32_b32 v34, -1, v34
	s_cbranch_scc1 .LBB0_462
	v_ashrrev_i32_e32 v35, 31, v34
	v_readlane_b32 s6, v254, 23
	v_lshlrev_b64 v[36:37], 4, v[34:35]
	v_readlane_b32 s7, v254, 24
	s_ashr_i32 s5, s4, 31
	v_lshlrev_b32_e32 v38, 2, v34
	v_lshl_add_u64 v[18:19], s[6:7], 0, v[36:37]
	v_add_co_u32_e32 v30, vcc, 0x1000, v18
	global_load_dwordx4 v[2:5], v[18:19], off
	global_load_dwordx4 v[6:9], v[18:19], off offset:1024
	global_load_dwordx4 v[10:13], v[18:19], off offset:2048
	global_load_dwordx4 v[14:17], v[18:19], off offset:3072
	v_addc_co_u32_e32 v31, vcc, 0, v19, vcc
	global_load_dwordx4 v[18:21], v[30:31], off
	global_load_dwordx4 v[22:25], v[30:31], off offset:1024
	global_load_dwordx4 v[26:29], v[30:31], off offset:2048
	s_nop 0
	global_load_dwordx4 v[30:33], v[30:31], off offset:3072
	v_cmp_lt_i32_e32 vcc, v233, v227
	v_readlane_b32 s6, v254, 19
	v_readlane_b32 s7, v254, 20
	v_cndmask_b32_e32 v0, v226, v233, vcc
	v_cmp_lt_i32_e32 vcc, v232, v227
	v_lshlrev_b32_e32 v140, 2, v0
	v_lshl_add_u64 v[98:99], s[6:7], 0, v[36:37]
	v_cndmask_b32_e32 v0, v226, v232, vcc
	v_cmp_lt_i32_e32 vcc, v251, v227
	v_lshlrev_b32_e32 v141, 2, v0
	s_lshl_b64 s[6:7], s[4:5], 12
	v_cndmask_b32_e32 v0, v226, v251, vcc
	v_cmp_lt_i32_e32 vcc, v250, v227
	v_lshlrev_b32_e32 v142, 2, v0
	v_readlane_b32 s8, v252, 0
	v_cndmask_b32_e32 v0, v226, v250, vcc
	v_cmp_lt_i32_e32 vcc, v235, v227
	v_lshlrev_b32_e32 v143, 2, v0
	v_ashrrev_i32_e32 v39, 31, v38
	v_cndmask_b32_e32 v0, v226, v235, vcc
	v_cmp_lt_i32_e32 vcc, v225, v227
	v_lshlrev_b32_e32 v144, 2, v0
	v_readlane_b32 s9, v252, 1
	v_cndmask_b32_e32 v0, v226, v225, vcc
	s_add_u32 s6, s8, s6
	v_lshlrev_b32_e32 v145, 2, v0
	v_lshlrev_b64 v[100:101], 3, v[34:35]
	s_addc_u32 s7, s9, s7
	v_lshlrev_b64 v[102:103], 1, v[38:39]
	v_lshl_add_u64 v[170:171], s[6:7], 0, v[102:103]
	v_add_co_u32_e32 v170, vcc, 0x27a00000, v170
	s_nop 1
	v_addc_co_u32_e32 v171, vcc, 0, v171, vcc
	global_load_dwordx2 v[154:155], v[170:171], off
	global_load_dwordx2 v[156:157], v[170:171], off offset:512
	global_load_dwordx2 v[158:159], v[170:171], off offset:1024
	global_load_dwordx2 v[160:161], v[170:171], off offset:1536
	global_load_dwordx2 v[162:163], v[170:171], off offset:2048
	global_load_dwordx2 v[164:165], v[170:171], off offset:2560
	global_load_dwordx2 v[166:167], v[170:171], off offset:3072
	global_load_dwordx2 v[168:169], v[170:171], off offset:3584
	s_waitcnt vmcnt(0)
.LBB0_461:
	s_add_i32 s5, s4, 0xffffe000
	s_ashr_i32 s5, s5, 10
	s_add_i32 s5, s5, 1
	s_cmpk_gt_i32 s4, 0x1fff
	v_lshl_add_u64 v[34:35], s[6:7], 0, v[102:103]
	s_cselect_b32 s5, s5, 0
	v_add_co_u32_e32 v34, vcc, 0x27a00000, v34
	v_mad_i64_i32 v[36:37], s[8:9], s5, v245, v[98:99]
	s_nop 0
	v_addc_co_u32_e32 v35, vcc, 0, v35, vcc
	v_lshl_add_u64 v[170:171], v[34:35], 0, s[86:87]
	v_add_co_u32_e32 v70, vcc, 0x2000, v36
	s_nop 1
	v_addc_co_u32_e32 v71, vcc, 0, v37, vcc
	global_load_dwordx4 v[90:93], v[36:37], off
	global_load_dwordx4 v[82:85], v[36:37], off offset:1024
	global_load_dwordx4 v[94:97], v[70:71], off
	global_load_dwordx4 v[86:89], v[70:71], off offset:1024
	global_load_dwordx4 v[74:77], v[36:37], off offset:2048
	global_load_dwordx4 v[66:69], v[36:37], off offset:3072
	v_add_co_u32_e32 v38, vcc, s97, v36
	s_nop 1
	v_addc_co_u32_e32 v39, vcc, 0, v37, vcc
	v_add_co_u32_e32 v40, vcc, s91, v36
	s_nop 1
	v_addc_co_u32_e32 v41, vcc, 0, v37, vcc
	global_load_dwordx4 v[58:61], v[38:39], off
	global_load_dwordx4 v[50:53], v[38:39], off offset:1024
	global_load_dwordx4 v[62:65], v[40:41], off
	global_load_dwordx4 v[54:57], v[40:41], off offset:1024
	global_load_dwordx4 v[42:45], v[38:39], off offset:2048
	s_nop 0
	global_load_dwordx4 v[34:37], v[38:39], off offset:3072
	global_load_dwordx4 v[46:49], v[40:41], off offset:2048
	s_nop 0
	global_load_dwordx4 v[38:41], v[40:41], off offset:3072
	s_nop 0
	global_load_dwordx4 v[78:81], v[70:71], off offset:2048
	s_nop 0
	global_load_dwordx4 v[70:73], v[70:71], off offset:3072
	s_waitcnt vmcnt(24)
	v_mov_b64_e32 v[114:115], v[154:155]
	v_mov_b64_e32 v[116:117], v[156:157]
	v_mov_b64_e32 v[120:121], v[158:159]
	v_mov_b64_e32 v[104:105], v[160:161]
	v_mov_b64_e32 v[122:123], v[162:163]
	v_mov_b64_e32 v[146:147], v[164:165]
	v_mov_b64_e32 v[148:149], v[166:167]
	v_mov_b64_e32 v[108:109], v[168:169]
	global_load_dwordx2 v[154:155], v[170:171], off
	global_load_dwordx2 v[156:157], v[170:171], off offset:512
	global_load_dwordx2 v[158:159], v[170:171], off offset:1024
	global_load_dwordx2 v[160:161], v[170:171], off offset:1536
	global_load_dwordx2 v[162:163], v[170:171], off offset:2048
	global_load_dwordx2 v[164:165], v[170:171], off offset:2560
	global_load_dwordx2 v[166:167], v[170:171], off offset:3072
	global_load_dwordx2 v[168:169], v[170:171], off offset:3584
	v_lshlrev_b32_e32 v113, 16, v104
	v_and_b32_e32 v111, 0xffff0000, v104
	v_lshlrev_b32_e32 v118, 16, v105
	v_and_b32_e32 v119, 0xffff0000, v105
	v_lshlrev_b32_e32 v107, 16, v108
	v_and_b32_e32 v105, 0xffff0000, v108
	v_lshlrev_b32_e32 v108, 16, v109
	v_and_b32_e32 v109, 0xffff0000, v109
	v_and_b32_e32 v139, 0xffff0000, v115
	v_and_b32_e32 v137, 0xffff0000, v114
	v_lshlrev_b32_e32 v138, 16, v115
	v_mul_f32_e32 v0, v139, v139
	v_lshlrev_b32_e32 v136, 16, v114
	v_pk_fma_f32 v[114:115], v[138:139], v[138:139], v[0:1] op_sel_hi:[1,1,0]
	v_and_b32_e32 v135, 0xffff0000, v117
	v_and_b32_e32 v134, 0xffff0000, v116
	v_mul_f32_e32 v0, v137, v137
	v_lshlrev_b32_e32 v133, 16, v117
	v_lshlrev_b32_e32 v132, 16, v116
	v_pk_mul_f32 v[116:117], v[134:135], v[134:135]
	v_lshlrev_b32_e32 v128, 16, v120
	v_and_b32_e32 v129, 0xffff0000, v120
	v_lshlrev_b32_e32 v130, 16, v121
	v_and_b32_e32 v131, 0xffff0000, v121
	v_pk_fma_f32 v[120:121], v[136:137], v[136:137], v[0:1] op_sel_hi:[1,1,0]
	v_pk_fma_f32 v[116:117], v[132:133], v[132:133], v[116:117]
	v_mov_b32_e32 v112, v120
	v_mov_b32_e32 v124, v114
	v_mov_b32_e32 v125, v113
	v_mul_f32_e32 v104, v111, v111
	v_pk_add_f32 v[114:115], v[120:121], v[114:115]
	v_pk_mul_f32 v[120:121], v[112:113], v[124:125]
	v_pk_add_f32 v[116:117], v[116:117], v[116:117] op_sel:[0,1] op_sel_hi:[1,0]
	v_mov_b32_e32 v115, v121
	v_mov_b32_e32 v117, v104
	v_mul_f32_e32 v0, v129, v129
	v_pk_add_f32 v[114:115], v[114:115], v[116:117]
	v_pk_fma_f32 v[116:117], v[128:129], v[128:129], v[0:1] op_sel_hi:[1,1,0]
	v_mul_f32_e32 v0, v131, v131
	v_mul_f32_e32 v106, v118, v118
	v_mul_f32_e32 v110, v119, v119
	v_pk_fma_f32 v[120:121], v[130:131], v[130:131], v[0:1] op_sel_hi:[1,1,0]
	v_mov_b32_e32 v117, v106
	v_mov_b32_e32 v121, v110
	v_pk_add_f32 v[116:117], v[116:117], v[120:121]
	v_and_b32_e32 v127, 0xffff0000, v123
	v_and_b32_e32 v126, 0xffff0000, v122
	v_pk_add_f32 v[150:151], v[114:115], v[116:117]
	v_lshlrev_b32_e32 v125, 16, v123
	v_lshlrev_b32_e32 v124, 16, v122
	v_pk_mul_f32 v[114:115], v[126:127], v[126:127]
	v_and_b32_e32 v123, 0xffff0000, v147
	v_pk_fma_f32 v[114:115], v[124:125], v[124:125], v[114:115]
	v_and_b32_e32 v122, 0xffff0000, v146
	v_pk_add_f32 v[152:153], v[114:115], v[114:115] op_sel:[0,1] op_sel_hi:[1,0]
	v_lshlrev_b32_e32 v121, 16, v147
	v_lshlrev_b32_e32 v120, 16, v146
	v_pk_mul_f32 v[114:115], v[122:123], v[122:123]
	v_lshlrev_b32_e32 v116, 16, v149
	v_pk_fma_f32 v[146:147], v[120:121], v[120:121], v[114:115]
	v_lshlrev_b32_e32 v114, 16, v148
	v_and_b32_e32 v115, 0xffff0000, v148
	v_and_b32_e32 v117, 0xffff0000, v149
	v_pk_add_f32 v[148:149], v[150:151], v[150:151] op_sel:[0,1] op_sel_hi:[1,0]
	v_mov_b32_e32 v150, v152
	v_mov_b32_e32 v106, v148
	v_mov_b32_e32 v151, v107
	v_mul_f32_e32 v0, v105, v105
	v_pk_add_f32 v[148:149], v[148:149], v[152:153]
	v_pk_mul_f32 v[150:151], v[106:107], v[150:151]
	v_pk_add_f32 v[146:147], v[146:147], v[146:147] op_sel:[0,1] op_sel_hi:[1,0]
	v_mov_b32_e32 v149, v151
	v_mov_b32_e32 v147, v0
	v_mul_f32_e32 v0, v115, v115
	v_pk_add_f32 v[146:147], v[148:149], v[146:147]
	v_pk_fma_f32 v[148:149], v[114:115], v[114:115], v[0:1] op_sel_hi:[1,1,0]
	v_mul_f32_e32 v0, v117, v117
	v_mul_f32_e32 v104, v108, v108
	v_mul_f32_e32 v110, v109, v109
	v_pk_fma_f32 v[150:151], v[116:117], v[116:117], v[0:1] op_sel_hi:[1,1,0]
	v_mov_b32_e32 v149, v104
	v_mov_b32_e32 v151, v110
	v_pk_add_f32 v[148:149], v[148:149], v[150:151]
	s_waitcnt vmcnt(14)
	v_pk_add_f32 v[94:95], v[94:95], 1.0 op_sel_hi:[1,0]
	v_pk_add_f32 v[146:147], v[146:147], v[148:149]
	v_pk_add_f32 v[96:97], v[96:97], 1.0 op_sel_hi:[1,0]
	v_add_f32_e32 v0, v146, v147
	v_lshl_add_u64 v[146:147], s[6:7], 0, v[100:101]
	v_pk_add_f32 v[88:89], v[88:89], 1.0 op_sel_hi:[1,0]
	v_pk_add_f32 v[86:87], v[86:87], 1.0 op_sel_hi:[1,0]
	s_waitcnt vmcnt(9)
	v_pk_add_f32 v[80:81], v[80:81], 1.0 op_sel_hi:[1,0]
	s_nop 1
	v_add_f32_dpp v0, v0, v0 quad_perm:[1,0,3,2] row_mask:0xf bank_mask:0xf
	v_pk_add_f32 v[78:79], v[78:79], 1.0 op_sel_hi:[1,0]
	v_mov_b32_e32 v110, v113
	s_waitcnt vmcnt(8)
	v_pk_add_f32 v[72:73], v[72:73], 1.0 op_sel_hi:[1,0]
	v_pk_add_f32 v[70:71], v[70:71], 1.0 op_sel_hi:[1,0]
	s_nop 1
	v_add_f32_dpp v0, v0, v0 quad_perm:[2,3,0,1] row_mask:0xf bank_mask:0xf
	v_pk_add_f32 v[64:65], v[64:65], 1.0 op_sel_hi:[1,0]
	v_pk_add_f32 v[62:63], v[62:63], 1.0 op_sel_hi:[1,0]
	v_pk_add_f32 v[56:57], v[56:57], 1.0 op_sel_hi:[1,0]
	v_pk_add_f32 v[54:55], v[54:55], 1.0 op_sel_hi:[1,0]
	s_nop 1
	v_add_f32_dpp v0, v0, v0 row_half_mirror row_mask:0xf bank_mask:0xf
	v_pk_add_f32 v[48:49], v[48:49], 1.0 op_sel_hi:[1,0]
	v_pk_add_f32 v[46:47], v[46:47], 1.0 op_sel_hi:[1,0]
	v_readlane_b32 s8, v254, 13
	s_add_i32 s4, s4, s8
	s_nop 1
	v_add_f32_dpp v0, v0, v0 row_mirror row_mask:0xf bank_mask:0xf
	v_pk_add_f32 v[40:41], v[40:41], 1.0 op_sel_hi:[1,0]
	v_pk_add_f32 v[38:39], v[38:39], 1.0 op_sel_hi:[1,0]
	s_add_u32 s6, s6, s86
	s_addc_u32 s7, s7, s87
	v_mov_b32_e32 v104, v0
	s_nop 1
	v_permlane16_swap_b32 v0, v104
	v_add_f32_e32 v0, v0, v104
	s_cmpk_lt_i32 s4, 0x2800
	v_readlane_b32 s9, v254, 14
	v_mov_b32_e32 v104, v0
	s_nop 1
	v_permlane32_swap_b32 v0, v104
	v_add_f32_e32 v0, v0, v104
	v_fmamk_f32 v0, v0, 0x3a000000, v224
	v_rsq_f32_e32 v0, v0
	v_mov_b32_e32 v104, v107
	v_pk_mul_f32 v[136:137], v[0:1], v[136:137] op_sel_hi:[0,1]
	v_pk_mul_f32 v[138:139], v[0:1], v[138:139] op_sel_hi:[0,1]
	v_pk_mul_f32 v[136:137], v[2:3], v[136:137]
	v_pk_mul_f32 v[138:139], v[4:5], v[138:139]
	v_pk_fma_f32 v[90:91], v[94:95], v[136:137], v[90:91]
	v_pk_fma_f32 v[92:93], v[96:97], v[138:139], v[92:93]
	v_cvt_pk_bf16_f32 v94, v90, v91
	v_add_co_u32_e32 v90, vcc, s51, v146
	v_cvt_pk_bf16_f32 v95, v92, v93
	s_nop 0
	v_addc_co_u32_e32 v91, vcc, 0, v147, vcc
	v_mov_b32_e32 v92, v133
	v_mov_b32_e32 v93, v135
	v_mov_b32_e32 v133, v134
	global_store_dwordx2 v[90:91], v[94:95], off
	v_pk_mul_f32 v[92:93], v[0:1], v[92:93] op_sel_hi:[0,1]
	v_pk_mul_f32 v[94:95], v[0:1], v[132:133] op_sel_hi:[0,1]
	v_pk_mul_f32 v[94:95], v[6:7], v[94:95]
	v_pk_mul_f32 v[92:93], v[8:9], v[92:93]
	v_pk_fma_f32 v[82:83], v[86:87], v[94:95], v[82:83]
	v_pk_fma_f32 v[84:85], v[88:89], v[92:93], v[84:85]
	v_cvt_pk_bf16_f32 v82, v82, v83
	v_cvt_pk_bf16_f32 v83, v84, v85
	global_store_dwordx2 v[90:91], v[82:83], off offset:512
	v_pk_mul_f32 v[82:83], v[0:1], v[130:131] op_sel_hi:[0,1]
	v_pk_mul_f32 v[84:85], v[0:1], v[128:129] op_sel_hi:[0,1]
	v_pk_mul_f32 v[84:85], v[10:11], v[84:85]
	v_pk_mul_f32 v[82:83], v[12:13], v[82:83]
	v_pk_fma_f32 v[74:75], v[78:79], v[84:85], v[74:75]
	v_pk_fma_f32 v[76:77], v[80:81], v[82:83], v[76:77]
	v_cvt_pk_bf16_f32 v74, v74, v75
	v_cvt_pk_bf16_f32 v75, v76, v77
	global_store_dwordx2 v[90:91], v[74:75], off offset:1024
	v_pk_mul_f32 v[74:75], v[118:119], v[0:1] op_sel_hi:[1,0]
	v_pk_mul_f32 v[76:77], v[110:111], v[0:1] op_sel_hi:[1,0]
	v_pk_mul_f32 v[74:75], v[16:17], v[74:75]
	v_pk_mul_f32 v[76:77], v[14:15], v[76:77]
	v_pk_fma_f32 v[68:69], v[72:73], v[74:75], v[68:69]
	v_pk_fma_f32 v[66:67], v[70:71], v[76:77], v[66:67]
	s_nop 0
	v_cvt_pk_bf16_f32 v66, v66, v67
	v_cvt_pk_bf16_f32 v67, v68, v69
	global_store_dwordx2 v[90:91], v[66:67], off offset:1536
	v_mov_b32_e32 v66, v125
	v_mov_b32_e32 v67, v127
	v_mov_b32_e32 v125, v126
	v_pk_mul_f32 v[66:67], v[0:1], v[66:67] op_sel_hi:[0,1]
	v_pk_mul_f32 v[68:69], v[0:1], v[124:125] op_sel_hi:[0,1]
	v_pk_mul_f32 v[68:69], v[18:19], v[68:69]
	v_pk_mul_f32 v[66:67], v[20:21], v[66:67]
	v_pk_fma_f32 v[58:59], v[62:63], v[68:69], v[58:59]
	v_pk_fma_f32 v[60:61], v[64:65], v[66:67], v[60:61]
	v_cvt_pk_bf16_f32 v58, v58, v59
	v_cvt_pk_bf16_f32 v59, v60, v61
	global_store_dwordx2 v[90:91], v[58:59], off offset:2048
	v_mov_b32_e32 v58, v121
	v_mov_b32_e32 v59, v123
	v_mov_b32_e32 v121, v122
	v_pk_mul_f32 v[58:59], v[0:1], v[58:59] op_sel_hi:[0,1]
	v_pk_mul_f32 v[60:61], v[0:1], v[120:121] op_sel_hi:[0,1]
	v_pk_mul_f32 v[60:61], v[22:23], v[60:61]
	v_pk_mul_f32 v[58:59], v[24:25], v[58:59]
	v_pk_fma_f32 v[50:51], v[54:55], v[60:61], v[50:51]
	v_pk_fma_f32 v[52:53], v[56:57], v[58:59], v[52:53]
	v_cvt_pk_bf16_f32 v50, v50, v51
	v_cvt_pk_bf16_f32 v51, v52, v53
	global_store_dwordx2 v[90:91], v[50:51], off offset:2560
	v_pk_mul_f32 v[50:51], v[0:1], v[116:117] op_sel_hi:[0,1]
	v_pk_mul_f32 v[52:53], v[0:1], v[114:115] op_sel_hi:[0,1]
	v_pk_mul_f32 v[52:53], v[26:27], v[52:53]
	v_pk_mul_f32 v[50:51], v[28:29], v[50:51]
	v_pk_fma_f32 v[42:43], v[46:47], v[52:53], v[42:43]
	v_pk_fma_f32 v[44:45], v[48:49], v[50:51], v[44:45]
	v_cvt_pk_bf16_f32 v42, v42, v43
	v_cvt_pk_bf16_f32 v43, v44, v45
	global_store_dwordx2 v[90:91], v[42:43], off offset:3072
	v_pk_mul_f32 v[42:43], v[108:109], v[0:1] op_sel_hi:[1,0]
	v_pk_mul_f32 v[44:45], v[104:105], v[0:1] op_sel_hi:[1,0]
	v_pk_mul_f32 v[42:43], v[32:33], v[42:43]
	v_pk_mul_f32 v[44:45], v[30:31], v[44:45]
	v_pk_fma_f32 v[36:37], v[40:41], v[42:43], v[36:37]
	v_pk_fma_f32 v[34:35], v[38:39], v[44:45], v[34:35]
	s_nop 0
	v_cvt_pk_bf16_f32 v34, v34, v35
	v_cvt_pk_bf16_f32 v35, v36, v37
	global_store_dwordx2 v[90:91], v[34:35], off offset:3584
	s_cbranch_scc1 .LBB0_461

.LBB0_989:
	s_and_b64 vcc, exec, s[4:5]
	s_cbranch_vccz .LBB0_1598
	v_readlane_b32 s4, v252, 16
	v_readlane_b32 s5, v252, 12
	s_lshl_b32 s5, s5, 3
	s_add_i32 s8, s5, s4
	s_cmpk_gt_i32 s8, 0x27ff
	v_mbcnt_lo_u32_b32 v34, -1, 0
	v_mbcnt_hi_u32_b32 v34, -1, v34
	s_cbranch_scc1 .LBB0_993
	v_ashrrev_i32_e32 v35, 31, v34
	v_readlane_b32 s4, v254, 23
	v_lshlrev_b64 v[36:37], 4, v[34:35]
	v_readlane_b32 s5, v254, 24
	s_ashr_i32 s9, s8, 31
	v_lshlrev_b32_e32 v38, 2, v34
	v_lshl_add_u64 v[18:19], s[4:5], 0, v[36:37]
	v_add_co_u32_e32 v10, vcc, 0x2000, v18
	s_mov_b64 s[4:5], 0x2000
	s_nop 0
	v_addc_co_u32_e32 v11, vcc, 0, v19, vcc
	v_add_co_u32_e32 v30, vcc, 0x3000, v18
	v_lshl_add_u64 v[14:15], v[18:19], 0, s[4:5]
	s_nop 0
	v_addc_co_u32_e32 v31, vcc, 0, v19, vcc
	global_load_dwordx4 v[2:5], v[14:15], off offset:1024
	global_load_dwordx4 v[6:9], v[14:15], off offset:2048
	s_nop 0
	global_load_dwordx4 v[10:13], v[10:11], off
	s_nop 0
	global_load_dwordx4 v[14:17], v[14:15], off offset:3072
	s_nop 0
	global_load_dwordx4 v[18:21], v[30:31], off
	global_load_dwordx4 v[22:25], v[30:31], off offset:1024
	global_load_dwordx4 v[26:29], v[30:31], off offset:2048
	s_nop 0
	global_load_dwordx4 v[30:33], v[30:31], off offset:3072
	v_cmp_lt_i32_e32 vcc, v233, v227
	v_readlane_b32 s4, v254, 19
	v_readlane_b32 s5, v254, 20
	v_cndmask_b32_e32 v0, v226, v233, vcc
	v_cmp_lt_i32_e32 vcc, v232, v227
	v_lshlrev_b32_e32 v140, 2, v0
	v_lshl_add_u64 v[36:37], s[4:5], 0, v[36:37]
	v_cndmask_b32_e32 v0, v226, v232, vcc
	v_cmp_lt_i32_e32 vcc, v251, v227
	v_lshlrev_b32_e32 v141, 2, v0
	s_mov_b64 s[4:5], 0x6000
	v_cndmask_b32_e32 v0, v226, v251, vcc
	v_cmp_lt_i32_e32 vcc, v250, v227
	v_lshlrev_b32_e32 v142, 2, v0
	v_lshl_add_u64 v[98:99], v[36:37], 0, s[4:5]
	v_cndmask_b32_e32 v0, v226, v250, vcc
	v_cmp_lt_i32_e32 vcc, v235, v227
	v_lshlrev_b32_e32 v143, 2, v0
	s_lshl_b64 s[4:5], s[8:9], 12
	v_cndmask_b32_e32 v0, v226, v235, vcc
	v_cmp_lt_i32_e32 vcc, v225, v227
	v_readlane_b32 s6, v252, 0
	v_ashrrev_i32_e32 v39, 31, v38
	v_lshlrev_b32_e32 v144, 2, v0
	v_cndmask_b32_e32 v0, v226, v225, vcc
	v_readlane_b32 s7, v252, 1
	s_add_u32 s10, s6, s4
	v_lshlrev_b32_e32 v145, 2, v0
	v_lshlrev_b64 v[100:101], 3, v[34:35]
	s_addc_u32 s11, s7, s5
	v_lshlrev_b64 v[102:103], 1, v[38:39]
	v_lshl_add_u64 v[170:171], s[10:11], 0, v[102:103]
	v_add_co_u32_e32 v170, vcc, 0x27a00000, v170
	s_nop 1
	v_addc_co_u32_e32 v171, vcc, 0, v171, vcc
	global_load_dwordx2 v[154:155], v[170:171], off
	global_load_dwordx2 v[156:157], v[170:171], off offset:512
	global_load_dwordx2 v[158:159], v[170:171], off offset:1024
	global_load_dwordx2 v[160:161], v[170:171], off offset:1536
	global_load_dwordx2 v[162:163], v[170:171], off offset:2048
	global_load_dwordx2 v[164:165], v[170:171], off offset:2560
	global_load_dwordx2 v[166:167], v[170:171], off offset:3072
	global_load_dwordx2 v[168:169], v[170:171], off offset:3584
	s_waitcnt vmcnt(0)
.LBB0_992:
	s_add_i32 s4, s8, 0xffffe000
	s_ashr_i32 s4, s4, 10
	s_add_i32 s4, s4, 1
	s_cmpk_gt_i32 s8, 0x1fff
	v_lshl_add_u64 v[34:35], s[10:11], 0, v[102:103]
	s_cselect_b32 s4, s4, 0
	v_add_co_u32_e32 v34, vcc, 0x27a00000, v34
	v_mad_i64_i32 v[36:37], s[4:5], s4, v245, v[98:99]
	s_nop 0
	v_addc_co_u32_e32 v35, vcc, 0, v35, vcc
	v_lshl_add_u64 v[170:171], v[34:35], 0, s[86:87]
	v_add_co_u32_e32 v70, vcc, 0x2000, v36
	s_nop 1
	v_addc_co_u32_e32 v71, vcc, 0, v37, vcc
	global_load_dwordx4 v[90:93], v[36:37], off
	global_load_dwordx4 v[82:85], v[36:37], off offset:1024
	global_load_dwordx4 v[94:97], v[70:71], off
	global_load_dwordx4 v[86:89], v[70:71], off offset:1024
	global_load_dwordx4 v[74:77], v[36:37], off offset:2048
	global_load_dwordx4 v[66:69], v[36:37], off offset:3072
	v_add_co_u32_e32 v38, vcc, s97, v36
	s_nop 1
	v_addc_co_u32_e32 v39, vcc, 0, v37, vcc
	v_add_co_u32_e32 v40, vcc, s91, v36
	s_nop 1
	v_addc_co_u32_e32 v41, vcc, 0, v37, vcc
	global_load_dwordx4 v[58:61], v[38:39], off
	global_load_dwordx4 v[50:53], v[38:39], off offset:1024
	global_load_dwordx4 v[62:65], v[40:41], off
	global_load_dwordx4 v[54:57], v[40:41], off offset:1024
	global_load_dwordx4 v[42:45], v[38:39], off offset:2048
	s_nop 0
	global_load_dwordx4 v[34:37], v[38:39], off offset:3072
	global_load_dwordx4 v[46:49], v[40:41], off offset:2048
	s_nop 0
	global_load_dwordx4 v[38:41], v[40:41], off offset:3072
	s_nop 0
	global_load_dwordx4 v[78:81], v[70:71], off offset:2048
	s_nop 0
	global_load_dwordx4 v[70:73], v[70:71], off offset:3072
	s_waitcnt vmcnt(24)
	v_mov_b64_e32 v[114:115], v[154:155]
	v_mov_b64_e32 v[116:117], v[156:157]
	v_mov_b64_e32 v[120:121], v[158:159]
	v_mov_b64_e32 v[104:105], v[160:161]
	v_mov_b64_e32 v[122:123], v[162:163]
	v_mov_b64_e32 v[146:147], v[164:165]
	v_mov_b64_e32 v[148:149], v[166:167]
	v_mov_b64_e32 v[108:109], v[168:169]
	global_load_dwordx2 v[154:155], v[170:171], off
	global_load_dwordx2 v[156:157], v[170:171], off offset:512
	global_load_dwordx2 v[158:159], v[170:171], off offset:1024
	global_load_dwordx2 v[160:161], v[170:171], off offset:1536
	global_load_dwordx2 v[162:163], v[170:171], off offset:2048
	global_load_dwordx2 v[164:165], v[170:171], off offset:2560
	global_load_dwordx2 v[166:167], v[170:171], off offset:3072
	global_load_dwordx2 v[168:169], v[170:171], off offset:3584
	v_lshlrev_b32_e32 v113, 16, v104
	v_and_b32_e32 v111, 0xffff0000, v104
	v_lshlrev_b32_e32 v118, 16, v105
	v_and_b32_e32 v119, 0xffff0000, v105
	v_lshlrev_b32_e32 v107, 16, v108
	v_and_b32_e32 v105, 0xffff0000, v108
	v_lshlrev_b32_e32 v108, 16, v109
	v_and_b32_e32 v109, 0xffff0000, v109
	v_and_b32_e32 v139, 0xffff0000, v115
	v_and_b32_e32 v137, 0xffff0000, v114
	v_lshlrev_b32_e32 v138, 16, v115
	v_mul_f32_e32 v0, v139, v139
	v_lshlrev_b32_e32 v136, 16, v114
	v_pk_fma_f32 v[114:115], v[138:139], v[138:139], v[0:1] op_sel_hi:[1,1,0]
	v_and_b32_e32 v135, 0xffff0000, v117
	v_and_b32_e32 v134, 0xffff0000, v116
	v_mul_f32_e32 v0, v137, v137
	v_lshlrev_b32_e32 v133, 16, v117
	v_lshlrev_b32_e32 v132, 16, v116
	v_pk_mul_f32 v[116:117], v[134:135], v[134:135]
	v_lshlrev_b32_e32 v128, 16, v120
	v_and_b32_e32 v129, 0xffff0000, v120
	v_lshlrev_b32_e32 v130, 16, v121
	v_and_b32_e32 v131, 0xffff0000, v121
	v_pk_fma_f32 v[120:121], v[136:137], v[136:137], v[0:1] op_sel_hi:[1,1,0]
	v_pk_fma_f32 v[116:117], v[132:133], v[132:133], v[116:117]
	v_mov_b32_e32 v112, v120
	v_mov_b32_e32 v124, v114
	v_mov_b32_e32 v125, v113
	v_mul_f32_e32 v104, v111, v111
	v_pk_add_f32 v[114:115], v[120:121], v[114:115]
	v_pk_mul_f32 v[120:121], v[112:113], v[124:125]
	v_pk_add_f32 v[116:117], v[116:117], v[116:117] op_sel:[0,1] op_sel_hi:[1,0]
	v_mov_b32_e32 v115, v121
	v_mov_b32_e32 v117, v104
	v_mul_f32_e32 v0, v129, v129
	v_pk_add_f32 v[114:115], v[114:115], v[116:117]
	v_pk_fma_f32 v[116:117], v[128:129], v[128:129], v[0:1] op_sel_hi:[1,1,0]
	v_mul_f32_e32 v0, v131, v131
	v_mul_f32_e32 v106, v118, v118
	v_mul_f32_e32 v110, v119, v119
	v_pk_fma_f32 v[120:121], v[130:131], v[130:131], v[0:1] op_sel_hi:[1,1,0]
	v_mov_b32_e32 v117, v106
	v_mov_b32_e32 v121, v110
	v_pk_add_f32 v[116:117], v[116:117], v[120:121]
	v_and_b32_e32 v127, 0xffff0000, v123
	v_and_b32_e32 v126, 0xffff0000, v122
	v_pk_add_f32 v[150:151], v[114:115], v[116:117]
	v_lshlrev_b32_e32 v125, 16, v123
	v_lshlrev_b32_e32 v124, 16, v122
	v_pk_mul_f32 v[114:115], v[126:127], v[126:127]
	v_and_b32_e32 v123, 0xffff0000, v147
	v_pk_fma_f32 v[114:115], v[124:125], v[124:125], v[114:115]
	v_and_b32_e32 v122, 0xffff0000, v146
	v_pk_add_f32 v[152:153], v[114:115], v[114:115] op_sel:[0,1] op_sel_hi:[1,0]
	v_lshlrev_b32_e32 v121, 16, v147
	v_lshlrev_b32_e32 v120, 16, v146
	v_pk_mul_f32 v[114:115], v[122:123], v[122:123]
	v_lshlrev_b32_e32 v116, 16, v149
	v_pk_fma_f32 v[146:147], v[120:121], v[120:121], v[114:115]
	v_lshlrev_b32_e32 v114, 16, v148
	v_and_b32_e32 v115, 0xffff0000, v148
	v_and_b32_e32 v117, 0xffff0000, v149
	v_pk_add_f32 v[148:149], v[150:151], v[150:151] op_sel:[0,1] op_sel_hi:[1,0]
	v_mov_b32_e32 v150, v152
	v_mov_b32_e32 v106, v148
	v_mov_b32_e32 v151, v107
	v_mul_f32_e32 v0, v105, v105
	v_pk_add_f32 v[148:149], v[148:149], v[152:153]
	v_pk_mul_f32 v[150:151], v[106:107], v[150:151]
	v_pk_add_f32 v[146:147], v[146:147], v[146:147] op_sel:[0,1] op_sel_hi:[1,0]
	v_mov_b32_e32 v149, v151
	v_mov_b32_e32 v147, v0
	v_mul_f32_e32 v0, v115, v115
	v_pk_add_f32 v[146:147], v[148:149], v[146:147]
	v_pk_fma_f32 v[148:149], v[114:115], v[114:115], v[0:1] op_sel_hi:[1,1,0]
	v_mul_f32_e32 v0, v117, v117
	v_mul_f32_e32 v104, v108, v108
	v_mul_f32_e32 v110, v109, v109
	v_pk_fma_f32 v[150:151], v[116:117], v[116:117], v[0:1] op_sel_hi:[1,1,0]
	v_mov_b32_e32 v149, v104
	v_mov_b32_e32 v151, v110
	v_pk_add_f32 v[148:149], v[148:149], v[150:151]
	s_waitcnt vmcnt(14)
	v_pk_add_f32 v[94:95], v[94:95], 1.0 op_sel_hi:[1,0]
	v_pk_add_f32 v[146:147], v[146:147], v[148:149]
	v_pk_add_f32 v[96:97], v[96:97], 1.0 op_sel_hi:[1,0]
	v_add_f32_e32 v0, v146, v147
	v_lshl_add_u64 v[146:147], s[10:11], 0, v[100:101]
	v_pk_add_f32 v[88:89], v[88:89], 1.0 op_sel_hi:[1,0]
	v_pk_add_f32 v[86:87], v[86:87], 1.0 op_sel_hi:[1,0]
	s_waitcnt vmcnt(9)
	v_pk_add_f32 v[80:81], v[80:81], 1.0 op_sel_hi:[1,0]
	s_nop 1
	v_add_f32_dpp v0, v0, v0 quad_perm:[1,0,3,2] row_mask:0xf bank_mask:0xf
	v_pk_add_f32 v[78:79], v[78:79], 1.0 op_sel_hi:[1,0]
	v_mov_b32_e32 v110, v113
	s_waitcnt vmcnt(8)
	v_pk_add_f32 v[72:73], v[72:73], 1.0 op_sel_hi:[1,0]
	v_pk_add_f32 v[70:71], v[70:71], 1.0 op_sel_hi:[1,0]
	s_nop 1
	v_add_f32_dpp v0, v0, v0 quad_perm:[2,3,0,1] row_mask:0xf bank_mask:0xf
	v_pk_add_f32 v[64:65], v[64:65], 1.0 op_sel_hi:[1,0]
	v_pk_add_f32 v[62:63], v[62:63], 1.0 op_sel_hi:[1,0]
	v_pk_add_f32 v[56:57], v[56:57], 1.0 op_sel_hi:[1,0]
	v_pk_add_f32 v[54:55], v[54:55], 1.0 op_sel_hi:[1,0]
	s_nop 1
	v_add_f32_dpp v0, v0, v0 row_half_mirror row_mask:0xf bank_mask:0xf
	v_pk_add_f32 v[48:49], v[48:49], 1.0 op_sel_hi:[1,0]
	v_pk_add_f32 v[46:47], v[46:47], 1.0 op_sel_hi:[1,0]
	v_readlane_b32 s4, v254, 13
	s_add_i32 s8, s8, s4
	s_nop 1
	v_add_f32_dpp v0, v0, v0 row_mirror row_mask:0xf bank_mask:0xf
	v_pk_add_f32 v[40:41], v[40:41], 1.0 op_sel_hi:[1,0]
	v_pk_add_f32 v[38:39], v[38:39], 1.0 op_sel_hi:[1,0]
	s_add_u32 s10, s10, s86
	s_addc_u32 s11, s11, s87
	v_mov_b32_e32 v104, v0
	s_nop 1
	v_permlane16_swap_b32 v0, v104
	v_add_f32_e32 v0, v0, v104
	s_cmpk_lt_i32 s8, 0x2800
	v_readlane_b32 s5, v254, 14
	v_mov_b32_e32 v104, v0
	s_nop 1
	v_permlane32_swap_b32 v0, v104
	v_add_f32_e32 v0, v0, v104
	v_fmamk_f32 v0, v0, 0x3a000000, v224
	v_rsq_f32_e32 v0, v0
	v_mov_b32_e32 v104, v107
	v_pk_mul_f32 v[136:137], v[0:1], v[136:137] op_sel_hi:[0,1]
	v_pk_mul_f32 v[138:139], v[0:1], v[138:139] op_sel_hi:[0,1]
	v_pk_mul_f32 v[136:137], v[10:11], v[136:137]
	v_pk_mul_f32 v[138:139], v[12:13], v[138:139]
	v_pk_fma_f32 v[90:91], v[94:95], v[136:137], v[90:91]
	v_pk_fma_f32 v[92:93], v[96:97], v[138:139], v[92:93]
	v_cvt_pk_bf16_f32 v94, v90, v91
	v_add_co_u32_e32 v90, vcc, s51, v146
	v_cvt_pk_bf16_f32 v95, v92, v93
	s_nop 0
	v_addc_co_u32_e32 v91, vcc, 0, v147, vcc
	v_mov_b32_e32 v92, v133
	v_mov_b32_e32 v93, v135
	v_mov_b32_e32 v133, v134
	global_store_dwordx2 v[90:91], v[94:95], off
	v_pk_mul_f32 v[92:93], v[0:1], v[92:93] op_sel_hi:[0,1]
	v_pk_mul_f32 v[94:95], v[0:1], v[132:133] op_sel_hi:[0,1]
	v_pk_mul_f32 v[94:95], v[2:3], v[94:95]
	v_pk_mul_f32 v[92:93], v[4:5], v[92:93]
	v_pk_fma_f32 v[82:83], v[86:87], v[94:95], v[82:83]
	v_pk_fma_f32 v[84:85], v[88:89], v[92:93], v[84:85]
	v_cvt_pk_bf16_f32 v82, v82, v83
	v_cvt_pk_bf16_f32 v83, v84, v85
	global_store_dwordx2 v[90:91], v[82:83], off offset:512
	v_pk_mul_f32 v[82:83], v[0:1], v[130:131] op_sel_hi:[0,1]
	v_pk_mul_f32 v[84:85], v[0:1], v[128:129] op_sel_hi:[0,1]
	v_pk_mul_f32 v[84:85], v[6:7], v[84:85]
	v_pk_mul_f32 v[82:83], v[8:9], v[82:83]
	v_pk_fma_f32 v[74:75], v[78:79], v[84:85], v[74:75]
	v_pk_fma_f32 v[76:77], v[80:81], v[82:83], v[76:77]
	v_cvt_pk_bf16_f32 v74, v74, v75
	v_cvt_pk_bf16_f32 v75, v76, v77
	global_store_dwordx2 v[90:91], v[74:75], off offset:1024
	v_pk_mul_f32 v[74:75], v[118:119], v[0:1] op_sel_hi:[1,0]
	v_pk_mul_f32 v[76:77], v[110:111], v[0:1] op_sel_hi:[1,0]
	v_pk_mul_f32 v[74:75], v[16:17], v[74:75]
	v_pk_mul_f32 v[76:77], v[14:15], v[76:77]
	v_pk_fma_f32 v[68:69], v[72:73], v[74:75], v[68:69]
	v_pk_fma_f32 v[66:67], v[70:71], v[76:77], v[66:67]
	s_nop 0
	v_cvt_pk_bf16_f32 v66, v66, v67
	v_cvt_pk_bf16_f32 v67, v68, v69
	global_store_dwordx2 v[90:91], v[66:67], off offset:1536
	v_mov_b32_e32 v66, v125
	v_mov_b32_e32 v67, v127
	v_mov_b32_e32 v125, v126
	v_pk_mul_f32 v[66:67], v[0:1], v[66:67] op_sel_hi:[0,1]
	v_pk_mul_f32 v[68:69], v[0:1], v[124:125] op_sel_hi:[0,1]
	v_pk_mul_f32 v[68:69], v[18:19], v[68:69]
	v_pk_mul_f32 v[66:67], v[20:21], v[66:67]
	v_pk_fma_f32 v[58:59], v[62:63], v[68:69], v[58:59]
	v_pk_fma_f32 v[60:61], v[64:65], v[66:67], v[60:61]
	v_cvt_pk_bf16_f32 v58, v58, v59
	v_cvt_pk_bf16_f32 v59, v60, v61
	global_store_dwordx2 v[90:91], v[58:59], off offset:2048
	v_mov_b32_e32 v58, v121
	v_mov_b32_e32 v59, v123
	v_mov_b32_e32 v121, v122
	v_pk_mul_f32 v[58:59], v[0:1], v[58:59] op_sel_hi:[0,1]
	v_pk_mul_f32 v[60:61], v[0:1], v[120:121] op_sel_hi:[0,1]
	v_pk_mul_f32 v[60:61], v[22:23], v[60:61]
	v_pk_mul_f32 v[58:59], v[24:25], v[58:59]
	v_pk_fma_f32 v[50:51], v[54:55], v[60:61], v[50:51]
	v_pk_fma_f32 v[52:53], v[56:57], v[58:59], v[52:53]
	v_cvt_pk_bf16_f32 v50, v50, v51
	v_cvt_pk_bf16_f32 v51, v52, v53
	global_store_dwordx2 v[90:91], v[50:51], off offset:2560
	v_pk_mul_f32 v[50:51], v[0:1], v[116:117] op_sel_hi:[0,1]
	v_pk_mul_f32 v[52:53], v[0:1], v[114:115] op_sel_hi:[0,1]
	v_pk_mul_f32 v[52:53], v[26:27], v[52:53]
	v_pk_mul_f32 v[50:51], v[28:29], v[50:51]
	v_pk_fma_f32 v[42:43], v[46:47], v[52:53], v[42:43]
	v_pk_fma_f32 v[44:45], v[48:49], v[50:51], v[44:45]
	v_cvt_pk_bf16_f32 v42, v42, v43
	v_cvt_pk_bf16_f32 v43, v44, v45
	global_store_dwordx2 v[90:91], v[42:43], off offset:3072
	v_pk_mul_f32 v[42:43], v[108:109], v[0:1] op_sel_hi:[1,0]
	v_pk_mul_f32 v[44:45], v[104:105], v[0:1] op_sel_hi:[1,0]
	v_pk_mul_f32 v[42:43], v[32:33], v[42:43]
	v_pk_mul_f32 v[44:45], v[30:31], v[44:45]
	v_pk_fma_f32 v[36:37], v[40:41], v[42:43], v[36:37]
	v_pk_fma_f32 v[34:35], v[38:39], v[44:45], v[34:35]
	s_nop 0
	v_cvt_pk_bf16_f32 v34, v34, v35
	v_cvt_pk_bf16_f32 v35, v36, v37
	global_store_dwordx2 v[90:91], v[34:35], off offset:3584
	s_cbranch_scc1 .LBB0_992

.LBB0_1598:
	v_readlane_b32 s4, v252, 16
	v_readlane_b32 s5, v252, 12
	s_lshl_b32 s5, s5, 3
	s_add_i32 s4, s5, s4
	s_cmpk_gt_i32 s4, 0x27ff
	s_waitcnt vmcnt(0)
	v_mbcnt_lo_u32_b32 v34, -1, 0
	v_mbcnt_hi_u32_b32 v34, -1, v34
	s_cbranch_scc1 .LBB0_1601
	v_ashrrev_i32_e32 v35, 31, v34
	v_readlane_b32 s6, v254, 23
	v_lshlrev_b64 v[36:37], 4, v[34:35]
	v_readlane_b32 s7, v254, 24
	s_ashr_i32 s5, s4, 31
	v_lshlrev_b32_e32 v38, 2, v34
	v_lshl_add_u64 v[18:19], s[6:7], 0, v[36:37]
	v_add_co_u32_e32 v10, vcc, 0x4000, v18
	s_mov_b64 s[6:7], 0x4000
	s_nop 0
	v_addc_co_u32_e32 v11, vcc, 0, v19, vcc
	v_add_co_u32_e32 v30, vcc, 0x5000, v18
	v_lshl_add_u64 v[14:15], v[18:19], 0, s[6:7]
	s_nop 0
	v_addc_co_u32_e32 v31, vcc, 0, v19, vcc
	global_load_dwordx4 v[2:5], v[14:15], off offset:1024
	global_load_dwordx4 v[6:9], v[14:15], off offset:2048
	s_nop 0
	global_load_dwordx4 v[10:13], v[10:11], off
	s_nop 0
	global_load_dwordx4 v[14:17], v[14:15], off offset:3072
	s_nop 0
	global_load_dwordx4 v[18:21], v[30:31], off
	global_load_dwordx4 v[22:25], v[30:31], off offset:1024
	global_load_dwordx4 v[26:29], v[30:31], off offset:2048
	s_nop 0
	global_load_dwordx4 v[30:33], v[30:31], off offset:3072
	v_cmp_lt_i32_e32 vcc, v233, v227
	v_readlane_b32 s6, v254, 19
	v_readlane_b32 s7, v254, 20
	v_cndmask_b32_e32 v0, v226, v233, vcc
	v_cmp_lt_i32_e32 vcc, v232, v227
	v_lshlrev_b32_e32 v140, 2, v0
	v_lshl_add_u64 v[36:37], s[6:7], 0, v[36:37]
	v_cndmask_b32_e32 v0, v226, v232, vcc
	v_cmp_lt_i32_e32 vcc, v251, v227
	v_lshlrev_b32_e32 v141, 2, v0
	s_mov_b64 s[6:7], 0xc000
	v_cndmask_b32_e32 v0, v226, v251, vcc
	v_cmp_lt_i32_e32 vcc, v250, v227
	v_lshlrev_b32_e32 v142, 2, v0
	v_lshl_add_u64 v[98:99], v[36:37], 0, s[6:7]
	v_cndmask_b32_e32 v0, v226, v250, vcc
	v_cmp_lt_i32_e32 vcc, v235, v227
	v_lshlrev_b32_e32 v143, 2, v0
	s_lshl_b64 s[6:7], s[4:5], 12
	v_cndmask_b32_e32 v0, v226, v235, vcc
	v_cmp_lt_i32_e32 vcc, v225, v227
	v_readlane_b32 s8, v252, 0
	v_ashrrev_i32_e32 v39, 31, v38
	v_lshlrev_b32_e32 v144, 2, v0
	v_cndmask_b32_e32 v0, v226, v225, vcc
	v_readlane_b32 s9, v252, 1
	s_add_u32 s8, s8, s6
	v_lshlrev_b32_e32 v145, 2, v0
	v_lshlrev_b64 v[100:101], 3, v[34:35]
	s_addc_u32 s9, s9, s7
	v_lshlrev_b64 v[102:103], 1, v[38:39]
	v_lshl_add_u64 v[170:171], s[8:9], 0, v[102:103]
	v_add_co_u32_e32 v170, vcc, 0x27a00000, v170
	s_nop 1
	v_addc_co_u32_e32 v171, vcc, 0, v171, vcc
	global_load_dwordx2 v[154:155], v[170:171], off
	global_load_dwordx2 v[156:157], v[170:171], off offset:512
	global_load_dwordx2 v[158:159], v[170:171], off offset:1024
	global_load_dwordx2 v[160:161], v[170:171], off offset:1536
	global_load_dwordx2 v[162:163], v[170:171], off offset:2048
	global_load_dwordx2 v[164:165], v[170:171], off offset:2560
	global_load_dwordx2 v[166:167], v[170:171], off offset:3072
	global_load_dwordx2 v[168:169], v[170:171], off offset:3584
	s_waitcnt vmcnt(0)
.LBB0_1600:
	s_add_i32 s5, s4, 0xffffe000
	s_ashr_i32 s5, s5, 10
	s_add_i32 s5, s5, 1
	s_cmpk_gt_i32 s4, 0x1fff
	v_lshl_add_u64 v[34:35], s[8:9], 0, v[102:103]
	s_cselect_b32 s5, s5, 0
	v_add_co_u32_e32 v34, vcc, 0x27a00000, v34
	v_mad_i64_i32 v[36:37], s[6:7], s5, v245, v[98:99]
	s_nop 0
	v_addc_co_u32_e32 v35, vcc, 0, v35, vcc
	v_lshl_add_u64 v[170:171], v[34:35], 0, s[86:87]
	v_add_co_u32_e32 v70, vcc, 0x2000, v36
	s_nop 1
	v_addc_co_u32_e32 v71, vcc, 0, v37, vcc
	global_load_dwordx4 v[90:93], v[36:37], off
	global_load_dwordx4 v[82:85], v[36:37], off offset:1024
	global_load_dwordx4 v[94:97], v[70:71], off
	global_load_dwordx4 v[86:89], v[70:71], off offset:1024
	global_load_dwordx4 v[74:77], v[36:37], off offset:2048
	global_load_dwordx4 v[66:69], v[36:37], off offset:3072
	v_add_co_u32_e32 v38, vcc, s97, v36
	s_nop 1
	v_addc_co_u32_e32 v39, vcc, 0, v37, vcc
	v_add_co_u32_e32 v40, vcc, s91, v36
	s_nop 1
	v_addc_co_u32_e32 v41, vcc, 0, v37, vcc
	global_load_dwordx4 v[58:61], v[38:39], off
	global_load_dwordx4 v[50:53], v[38:39], off offset:1024
	global_load_dwordx4 v[62:65], v[40:41], off
	global_load_dwordx4 v[54:57], v[40:41], off offset:1024
	global_load_dwordx4 v[42:45], v[38:39], off offset:2048
	s_nop 0
	global_load_dwordx4 v[34:37], v[38:39], off offset:3072
	global_load_dwordx4 v[46:49], v[40:41], off offset:2048
	s_nop 0
	global_load_dwordx4 v[38:41], v[40:41], off offset:3072
	s_nop 0
	global_load_dwordx4 v[78:81], v[70:71], off offset:2048
	s_nop 0
	global_load_dwordx4 v[70:73], v[70:71], off offset:3072
	s_waitcnt vmcnt(24)
	v_mov_b64_e32 v[114:115], v[154:155]
	v_mov_b64_e32 v[116:117], v[156:157]
	v_mov_b64_e32 v[120:121], v[158:159]
	v_mov_b64_e32 v[104:105], v[160:161]
	v_mov_b64_e32 v[122:123], v[162:163]
	v_mov_b64_e32 v[146:147], v[164:165]
	v_mov_b64_e32 v[148:149], v[166:167]
	v_mov_b64_e32 v[108:109], v[168:169]
	global_load_dwordx2 v[154:155], v[170:171], off
	global_load_dwordx2 v[156:157], v[170:171], off offset:512
	global_load_dwordx2 v[158:159], v[170:171], off offset:1024
	global_load_dwordx2 v[160:161], v[170:171], off offset:1536
	global_load_dwordx2 v[162:163], v[170:171], off offset:2048
	global_load_dwordx2 v[164:165], v[170:171], off offset:2560
	global_load_dwordx2 v[166:167], v[170:171], off offset:3072
	global_load_dwordx2 v[168:169], v[170:171], off offset:3584
	v_lshlrev_b32_e32 v113, 16, v104
	v_and_b32_e32 v111, 0xffff0000, v104
	v_lshlrev_b32_e32 v118, 16, v105
	v_and_b32_e32 v119, 0xffff0000, v105
	v_lshlrev_b32_e32 v107, 16, v108
	v_and_b32_e32 v105, 0xffff0000, v108
	v_lshlrev_b32_e32 v108, 16, v109
	v_and_b32_e32 v109, 0xffff0000, v109
	v_and_b32_e32 v139, 0xffff0000, v115
	v_and_b32_e32 v137, 0xffff0000, v114
	v_lshlrev_b32_e32 v138, 16, v115
	v_mul_f32_e32 v0, v139, v139
	v_lshlrev_b32_e32 v136, 16, v114
	v_pk_fma_f32 v[114:115], v[138:139], v[138:139], v[0:1] op_sel_hi:[1,1,0]
	v_and_b32_e32 v135, 0xffff0000, v117
	v_and_b32_e32 v134, 0xffff0000, v116
	v_mul_f32_e32 v0, v137, v137
	v_lshlrev_b32_e32 v133, 16, v117
	v_lshlrev_b32_e32 v132, 16, v116
	v_pk_mul_f32 v[116:117], v[134:135], v[134:135]
	v_lshlrev_b32_e32 v128, 16, v120
	v_and_b32_e32 v129, 0xffff0000, v120
	v_lshlrev_b32_e32 v130, 16, v121
	v_and_b32_e32 v131, 0xffff0000, v121
	v_pk_fma_f32 v[120:121], v[136:137], v[136:137], v[0:1] op_sel_hi:[1,1,0]
	v_pk_fma_f32 v[116:117], v[132:133], v[132:133], v[116:117]
	v_mov_b32_e32 v112, v120
	v_mov_b32_e32 v124, v114
	v_mov_b32_e32 v125, v113
	v_mul_f32_e32 v104, v111, v111
	v_pk_add_f32 v[114:115], v[120:121], v[114:115]
	v_pk_mul_f32 v[120:121], v[112:113], v[124:125]
	v_pk_add_f32 v[116:117], v[116:117], v[116:117] op_sel:[0,1] op_sel_hi:[1,0]
	v_mov_b32_e32 v115, v121
	v_mov_b32_e32 v117, v104
	v_mul_f32_e32 v0, v129, v129
	v_pk_add_f32 v[114:115], v[114:115], v[116:117]
	v_pk_fma_f32 v[116:117], v[128:129], v[128:129], v[0:1] op_sel_hi:[1,1,0]
	v_mul_f32_e32 v0, v131, v131
	v_mul_f32_e32 v106, v118, v118
	v_mul_f32_e32 v110, v119, v119
	v_pk_fma_f32 v[120:121], v[130:131], v[130:131], v[0:1] op_sel_hi:[1,1,0]
	v_mov_b32_e32 v117, v106
	v_mov_b32_e32 v121, v110
	v_pk_add_f32 v[116:117], v[116:117], v[120:121]
	v_and_b32_e32 v127, 0xffff0000, v123
	v_and_b32_e32 v126, 0xffff0000, v122
	v_pk_add_f32 v[150:151], v[114:115], v[116:117]
	v_lshlrev_b32_e32 v125, 16, v123
	v_lshlrev_b32_e32 v124, 16, v122
	v_pk_mul_f32 v[114:115], v[126:127], v[126:127]
	v_and_b32_e32 v123, 0xffff0000, v147
	v_pk_fma_f32 v[114:115], v[124:125], v[124:125], v[114:115]
	v_and_b32_e32 v122, 0xffff0000, v146
	v_pk_add_f32 v[152:153], v[114:115], v[114:115] op_sel:[0,1] op_sel_hi:[1,0]
	v_lshlrev_b32_e32 v121, 16, v147
	v_lshlrev_b32_e32 v120, 16, v146
	v_pk_mul_f32 v[114:115], v[122:123], v[122:123]
	v_lshlrev_b32_e32 v116, 16, v149
	v_pk_fma_f32 v[146:147], v[120:121], v[120:121], v[114:115]
	v_lshlrev_b32_e32 v114, 16, v148
	v_and_b32_e32 v115, 0xffff0000, v148
	v_and_b32_e32 v117, 0xffff0000, v149
	v_pk_add_f32 v[148:149], v[150:151], v[150:151] op_sel:[0,1] op_sel_hi:[1,0]
	v_mov_b32_e32 v150, v152
	v_mov_b32_e32 v106, v148
	v_mov_b32_e32 v151, v107
	v_mul_f32_e32 v0, v105, v105
	v_pk_add_f32 v[148:149], v[148:149], v[152:153]
	v_pk_mul_f32 v[150:151], v[106:107], v[150:151]
	v_pk_add_f32 v[146:147], v[146:147], v[146:147] op_sel:[0,1] op_sel_hi:[1,0]
	v_mov_b32_e32 v149, v151
	v_mov_b32_e32 v147, v0
	v_mul_f32_e32 v0, v115, v115
	v_pk_add_f32 v[146:147], v[148:149], v[146:147]
	v_pk_fma_f32 v[148:149], v[114:115], v[114:115], v[0:1] op_sel_hi:[1,1,0]
	v_mul_f32_e32 v0, v117, v117
	v_mul_f32_e32 v104, v108, v108
	v_mul_f32_e32 v110, v109, v109
	v_pk_fma_f32 v[150:151], v[116:117], v[116:117], v[0:1] op_sel_hi:[1,1,0]
	v_mov_b32_e32 v149, v104
	v_mov_b32_e32 v151, v110
	v_pk_add_f32 v[148:149], v[148:149], v[150:151]
	s_waitcnt vmcnt(14)
	v_pk_add_f32 v[94:95], v[94:95], 1.0 op_sel_hi:[1,0]
	v_pk_add_f32 v[146:147], v[146:147], v[148:149]
	v_pk_add_f32 v[96:97], v[96:97], 1.0 op_sel_hi:[1,0]
	v_add_f32_e32 v0, v146, v147
	v_lshl_add_u64 v[146:147], s[8:9], 0, v[100:101]
	v_pk_add_f32 v[88:89], v[88:89], 1.0 op_sel_hi:[1,0]
	v_pk_add_f32 v[86:87], v[86:87], 1.0 op_sel_hi:[1,0]
	s_waitcnt vmcnt(9)
	v_pk_add_f32 v[80:81], v[80:81], 1.0 op_sel_hi:[1,0]
	s_nop 1
	v_add_f32_dpp v0, v0, v0 quad_perm:[1,0,3,2] row_mask:0xf bank_mask:0xf
	v_pk_add_f32 v[78:79], v[78:79], 1.0 op_sel_hi:[1,0]
	v_mov_b32_e32 v110, v113
	s_waitcnt vmcnt(8)
	v_pk_add_f32 v[72:73], v[72:73], 1.0 op_sel_hi:[1,0]
	v_pk_add_f32 v[70:71], v[70:71], 1.0 op_sel_hi:[1,0]
	s_nop 1
	v_add_f32_dpp v0, v0, v0 quad_perm:[2,3,0,1] row_mask:0xf bank_mask:0xf
	v_pk_add_f32 v[64:65], v[64:65], 1.0 op_sel_hi:[1,0]
	v_pk_add_f32 v[62:63], v[62:63], 1.0 op_sel_hi:[1,0]
	v_pk_add_f32 v[56:57], v[56:57], 1.0 op_sel_hi:[1,0]
	v_pk_add_f32 v[54:55], v[54:55], 1.0 op_sel_hi:[1,0]
	s_nop 1
	v_add_f32_dpp v0, v0, v0 row_half_mirror row_mask:0xf bank_mask:0xf
	v_pk_add_f32 v[48:49], v[48:49], 1.0 op_sel_hi:[1,0]
	v_pk_add_f32 v[46:47], v[46:47], 1.0 op_sel_hi:[1,0]
	v_readlane_b32 s6, v254, 13
	s_add_i32 s4, s4, s6
	s_nop 1
	v_add_f32_dpp v0, v0, v0 row_mirror row_mask:0xf bank_mask:0xf
	v_pk_add_f32 v[40:41], v[40:41], 1.0 op_sel_hi:[1,0]
	v_pk_add_f32 v[38:39], v[38:39], 1.0 op_sel_hi:[1,0]
	s_add_u32 s8, s8, s86
	s_addc_u32 s9, s9, s87
	v_mov_b32_e32 v104, v0
	s_nop 1
	v_permlane16_swap_b32 v0, v104
	v_add_f32_e32 v0, v0, v104
	s_cmpk_lt_i32 s4, 0x2800
	v_readlane_b32 s7, v254, 14
	v_mov_b32_e32 v104, v0
	s_nop 1
	v_permlane32_swap_b32 v0, v104
	v_add_f32_e32 v0, v0, v104
	v_fmamk_f32 v0, v0, 0x3a000000, v224
	v_rsq_f32_e32 v0, v0
	v_mov_b32_e32 v104, v107
	v_pk_mul_f32 v[136:137], v[0:1], v[136:137] op_sel_hi:[0,1]
	v_pk_mul_f32 v[138:139], v[0:1], v[138:139] op_sel_hi:[0,1]
	v_pk_mul_f32 v[136:137], v[10:11], v[136:137]
	v_pk_mul_f32 v[138:139], v[12:13], v[138:139]
	v_pk_fma_f32 v[90:91], v[94:95], v[136:137], v[90:91]
	v_pk_fma_f32 v[92:93], v[96:97], v[138:139], v[92:93]
	v_cvt_pk_bf16_f32 v94, v90, v91
	v_add_co_u32_e32 v90, vcc, s51, v146
	v_cvt_pk_bf16_f32 v95, v92, v93
	s_nop 0
	v_addc_co_u32_e32 v91, vcc, 0, v147, vcc
	v_mov_b32_e32 v92, v133
	v_mov_b32_e32 v93, v135
	v_mov_b32_e32 v133, v134
	global_store_dwordx2 v[90:91], v[94:95], off
	v_pk_mul_f32 v[92:93], v[0:1], v[92:93] op_sel_hi:[0,1]
	v_pk_mul_f32 v[94:95], v[0:1], v[132:133] op_sel_hi:[0,1]
	v_pk_mul_f32 v[94:95], v[2:3], v[94:95]
	v_pk_mul_f32 v[92:93], v[4:5], v[92:93]
	v_pk_fma_f32 v[82:83], v[86:87], v[94:95], v[82:83]
	v_pk_fma_f32 v[84:85], v[88:89], v[92:93], v[84:85]
	v_cvt_pk_bf16_f32 v82, v82, v83
	v_cvt_pk_bf16_f32 v83, v84, v85
	global_store_dwordx2 v[90:91], v[82:83], off offset:512
	v_pk_mul_f32 v[82:83], v[0:1], v[130:131] op_sel_hi:[0,1]
	v_pk_mul_f32 v[84:85], v[0:1], v[128:129] op_sel_hi:[0,1]
	v_pk_mul_f32 v[84:85], v[6:7], v[84:85]
	v_pk_mul_f32 v[82:83], v[8:9], v[82:83]
	v_pk_fma_f32 v[74:75], v[78:79], v[84:85], v[74:75]
	v_pk_fma_f32 v[76:77], v[80:81], v[82:83], v[76:77]
	v_cvt_pk_bf16_f32 v74, v74, v75
	v_cvt_pk_bf16_f32 v75, v76, v77
	global_store_dwordx2 v[90:91], v[74:75], off offset:1024
	v_pk_mul_f32 v[74:75], v[118:119], v[0:1] op_sel_hi:[1,0]
	v_pk_mul_f32 v[76:77], v[110:111], v[0:1] op_sel_hi:[1,0]
	v_pk_mul_f32 v[74:75], v[16:17], v[74:75]
	v_pk_mul_f32 v[76:77], v[14:15], v[76:77]
	v_pk_fma_f32 v[68:69], v[72:73], v[74:75], v[68:69]
	v_pk_fma_f32 v[66:67], v[70:71], v[76:77], v[66:67]
	s_nop 0
	v_cvt_pk_bf16_f32 v66, v66, v67
	v_cvt_pk_bf16_f32 v67, v68, v69
	global_store_dwordx2 v[90:91], v[66:67], off offset:1536
	v_mov_b32_e32 v66, v125
	v_mov_b32_e32 v67, v127
	v_mov_b32_e32 v125, v126
	v_pk_mul_f32 v[66:67], v[0:1], v[66:67] op_sel_hi:[0,1]
	v_pk_mul_f32 v[68:69], v[0:1], v[124:125] op_sel_hi:[0,1]
	v_pk_mul_f32 v[68:69], v[18:19], v[68:69]
	v_pk_mul_f32 v[66:67], v[20:21], v[66:67]
	v_pk_fma_f32 v[58:59], v[62:63], v[68:69], v[58:59]
	v_pk_fma_f32 v[60:61], v[64:65], v[66:67], v[60:61]
	v_cvt_pk_bf16_f32 v58, v58, v59
	v_cvt_pk_bf16_f32 v59, v60, v61
	global_store_dwordx2 v[90:91], v[58:59], off offset:2048
	v_mov_b32_e32 v58, v121
	v_mov_b32_e32 v59, v123
	v_mov_b32_e32 v121, v122
	v_pk_mul_f32 v[58:59], v[0:1], v[58:59] op_sel_hi:[0,1]
	v_pk_mul_f32 v[60:61], v[0:1], v[120:121] op_sel_hi:[0,1]
	v_pk_mul_f32 v[60:61], v[22:23], v[60:61]
	v_pk_mul_f32 v[58:59], v[24:25], v[58:59]
	v_pk_fma_f32 v[50:51], v[54:55], v[60:61], v[50:51]
	v_pk_fma_f32 v[52:53], v[56:57], v[58:59], v[52:53]
	v_cvt_pk_bf16_f32 v50, v50, v51
	v_cvt_pk_bf16_f32 v51, v52, v53
	global_store_dwordx2 v[90:91], v[50:51], off offset:2560
	v_pk_mul_f32 v[50:51], v[0:1], v[116:117] op_sel_hi:[0,1]
	v_pk_mul_f32 v[52:53], v[0:1], v[114:115] op_sel_hi:[0,1]
	v_pk_mul_f32 v[52:53], v[26:27], v[52:53]
	v_pk_mul_f32 v[50:51], v[28:29], v[50:51]
	v_pk_fma_f32 v[42:43], v[46:47], v[52:53], v[42:43]
	v_pk_fma_f32 v[44:45], v[48:49], v[50:51], v[44:45]
	v_cvt_pk_bf16_f32 v42, v42, v43
	v_cvt_pk_bf16_f32 v43, v44, v45
	global_store_dwordx2 v[90:91], v[42:43], off offset:3072
	v_pk_mul_f32 v[42:43], v[108:109], v[0:1] op_sel_hi:[1,0]
	v_pk_mul_f32 v[44:45], v[104:105], v[0:1] op_sel_hi:[1,0]
	v_pk_mul_f32 v[42:43], v[32:33], v[42:43]
	v_pk_mul_f32 v[44:45], v[30:31], v[44:45]
	v_pk_fma_f32 v[36:37], v[40:41], v[42:43], v[36:37]
	v_pk_fma_f32 v[34:35], v[38:39], v[44:45], v[34:35]
	s_nop 0
	v_cvt_pk_bf16_f32 v34, v34, v35
	v_cvt_pk_bf16_f32 v35, v36, v37
	global_store_dwordx2 v[90:91], v[34:35], off offset:3584
	s_cbranch_scc1 .LBB0_1600
